# layer-0 weight prep: same rebalancing (bias-item workgroups skip conversion items)
# speedup vs baseline: 1.0234x; 1.0014x over previous
; #define LAS __attribute__((address_space(3)))
; #define otid() ((wv << 6) | olane())
; __device__ __forceinline__ void tr_item(const float* W, int N, bf16_t* WT, int ldk, int row_off, int split, int shift, int ncopy, int copy_stride, LAS float* scr, int item, int lane) {
;     const int nblk = N / 32, kb = item / nblk, nb = item % nblk, k0 = 64 * kb, n0 = 32 * nb;
;     float wv_[32];
; #pragma unroll
;     for (int i = 0; i < 32; ++i) wv_[i] = W[(size_t)(k0 + 2 * i + (lane >> 5)) * N + n0 + (lane & 31)];
; __device__ __forceinline__ void convert_weights(LAS unsigned char* lds, KP p, int l, int wv) {
;     unsigned char* ws = p->ws;
;     const int tid_ = otid(); const int lane = tid_ & 63, wid = tid_ >> 6;
;     LAS float* scr = (LAS float*)(lds + wid * 8704);
;     const int gw = blockIdx.x * 8 + wid, NGW = gridDim.x * 8;
;     constexpr int I_IN = 16 * (DIN / 32), I_UQ = 6 * 24, I_UKV = 4 * 32, I_BR = 8 * 32, I_O = 16 * 32, I_F1 = 16 * 128, I_F2 = 64 * 32;
;     constexpr int NIT = I_IN + I_UQ + I_UKV + 3 * I_BR + I_O + I_F1 + I_F2;
;     const int BIG = 1 << 30;
;     for (int it = gw; it < NIT; it += NGW) {
;         int r = it;
;         if (r < I_IN) { tr_item(p->w_in + (size_t)l * DM * DIN, DIN, (bf16_t*)(ws + WS_WIN), DM, 0, NGATE0, NPM - NGATE0, 1, 0, scr, r, lane); continue; } r -= I_IN;
.Lp0_full:
	s_waitcnt lgkmcnt(0)
	v_readlane_b32 s8, v255, 0
	v_readlane_b32 s9, v255, 1
	s_mov_b32 s0, s79
	s_load_dwordx2 s[10:11], s[8:9], 0xd8
	v_mbcnt_lo_u32_b32 v0, -1, 0
	v_mbcnt_hi_u32_b32 v0, -1, v0
	s_sub_i32 s0, s79, 0x83
	s_lshl_b32 s0, s0, 3
	s_cmp_lt_u32 s79, 0x83
	s_cselect_b32 s0, 0x1460, s0
	v_or_b32_e32 v1, s82, v0
	v_ashrrev_i32_e32 v1, 6, v1
	s_mov_b32 s91, s77
	v_add_u32_e32 v18, s0, v1
	s_movk_i32 s0, 0x1460
	s_cmp_lg_u32 s90, 0
	s_cselect_b32 s0, s0, 0
	v_add_u32_e32 v18, s0, v18
	s_movk_i32 s0, 0x1460
	s_lshl_b64 s[12:13], s[90:91], 24
	s_mul_hi_u32 s28, s90, 0x20a0000
	s_mul_i32 s29, s90, 0x20a0000
	v_cmp_gt_i32_e32 vcc, s0, v18
	s_and_saveexec_b64 s[0:1], vcc
	s_cbranch_execz .LBB0_128
	s_movk_i32 s14, 0x2200
	v_bfe_u32 v19, v0, 5, 1
	v_and_b32_e32 v14, 31, v0
	v_bfe_u32 v21, v0, 3, 3
	v_lshlrev_b32_e32 v0, 3, v0
	v_mul_lo_u32 v1, v1, s14
	v_and_b32_e32 v0, 56, v0
	v_add_u32_e32 v4, 0, v1
	v_lshlrev_b32_e32 v1, 2, v14
	v_mul_u32_u24_e32 v2, 0x84, v19
	v_lshlrev_b32_e32 v192, 1, v0
	v_add3_u32 v20, v4, v1, v2
	v_mul_u32_u24_e32 v5, 0x84, v0
	s_waitcnt lgkmcnt(0)
	v_lshl_add_u64 v[0:1], s[10:11], 0, v[192:193]
	s_mov_b64 s[14:15], 0x2700000
	v_lshl_add_u64 v[2:3], v[0:1], 0, s[14:15]
	v_lshlrev_b32_e32 v6, 2, v21
	s_mov_b64 s[14:15], 0x1f00000
	v_add3_u32 v22, v4, v5, v6
	v_lshl_add_u64 v[4:5], v[0:1], 0, s[14:15]
	s_mov_b64 s[14:15], 0x1700000
	v_lshl_add_u64 v[6:7], v[0:1], 0, s[14:15]
	s_mov_b64 s[14:15], 0x1300000
	v_lshl_add_u64 v[8:9], v[0:1], 0, s[14:15]
	s_mov_b64 s[14:15], 0x1200000
	v_lshl_add_u64 v[10:11], v[0:1], 0, s[14:15]
	s_mov_b64 s[14:15], 0x1100000
	v_lshl_add_u64 v[12:13], v[0:1], 0, s[14:15]
	s_movk_i32 s14, 0x3e8
	v_readlane_b32 s15, v255, 30
	v_mov_b32_e32 v15, 0x1c340
	s_lshl_b64 s[2:3], s[90:91], 22
	s_lshl_b64 s[4:5], s[90:91], 23
	s_lshl_b64 s[6:7], s[90:91], 20
	v_or_b32_e32 v23, 8, v21
	v_or_b32_e32 v24, 16, v21
	v_or_b32_e32 v25, 24, v21
	v_lshlrev_b32_e32 v26, 5, v18
	s_lshl_b32 s30, s14, 5
	v_lshl_add_u32 v27, v18, 1, v15
	s_lshl_b32 s31, s14, 1
	s_mov_b64 s[14:15], 0
	v_lshlrev_b32_e32 v14, 2, v14
	v_add_u32_e32 v28, 0x400, v20
	v_add_u32_e32 v29, 0x800, v20
	v_add_u32_e32 v30, 0xc00, v20
	v_add_u32_e32 v31, 0x1000, v20
	v_add_u32_e32 v32, 0x1400, v20
	v_add_u32_e32 v33, 0x1800, v20
	v_add_u32_e32 v34, 0x1c00, v20
	s_branch .LBB0_100
.LBB0_99:
	s_or_b64 exec, exec, s[16:17]
	s_movk_i32 s16, 0x3e8
	v_add_u32_e32 v26, s30, v26
	v_add_u32_e32 v27, s31, v27
	v_add_u32_e32 v18, s16, v18
	s_movk_i32 s16, 0x145f
	v_cmp_lt_i32_e32 vcc, s16, v18
	s_or_b64 s[14:15], vcc, s[14:15]
	v_readlane_b32 s17, v255, 30
	s_andn2_b64 exec, exec, s[14:15]
	s_cbranch_execz .LBB0_128
